# attention PV counted-lgkmcnt ladder + over-drain vmcnt ladder removed on the load path (3 call sites)
# speedup vs baseline: 1.0058x; 1.0058x over previous
.LBB0_664:
	s_waitcnt lgkmcnt(0)
	ds_read_b64_tr_b16 v[180:181], v202 offset:0
	ds_read_b64_tr_b16 v[182:183], v202 offset:0x800
	ds_read_b64_tr_b16 v[210:211], v202 offset:0x1000
	ds_read_b64_tr_b16 v[212:213], v202 offset:0x1800
	ds_read_b64_tr_b16 v[238:239], v202 offset:0x2000
	ds_read_b64_tr_b16 v[240:241], v202 offset:0x2800
	ds_read_b64_tr_b16 v[242:243], v202 offset:0x3000
	ds_read_b64_tr_b16 v[244:245], v202 offset:0x3800
	s_nop 0
	s_waitcnt lgkmcnt(6)
	v_mfma_f32_32x32x16_bf16 v[0:15], v[160:163], v[180:183], v[0:15]
	ds_read_b64_tr_b16 v[180:181], v202 offset:0x200
	ds_read_b64_tr_b16 v[182:183], v202 offset:0xa00
	s_waitcnt lgkmcnt(6)
	v_mfma_f32_32x32x16_bf16 v[0:15], v[164:167], v[210:213], v[0:15]
	ds_read_b64_tr_b16 v[210:211], v202 offset:0x1200
	ds_read_b64_tr_b16 v[212:213], v202 offset:0x1a00
	s_waitcnt lgkmcnt(6)
	v_mfma_f32_32x32x16_bf16 v[0:15], v[168:171], v[238:241], v[0:15]
	ds_read_b64_tr_b16 v[238:239], v202 offset:0x2200
	ds_read_b64_tr_b16 v[240:241], v202 offset:0x2a00
	s_waitcnt lgkmcnt(6)
	v_mfma_f32_32x32x16_bf16 v[0:15], v[172:175], v[242:245], v[0:15]
	ds_read_b64_tr_b16 v[242:243], v202 offset:0x3200
	ds_read_b64_tr_b16 v[244:245], v202 offset:0x3a00
	s_waitcnt lgkmcnt(6)
	v_mfma_f32_32x32x16_bf16 v[48:63], v[160:163], v[180:183], v[48:63]
	ds_read_b64_tr_b16 v[180:181], v202 offset:0x400
	ds_read_b64_tr_b16 v[182:183], v202 offset:0xc00
	s_waitcnt lgkmcnt(6)
	v_mfma_f32_32x32x16_bf16 v[48:63], v[164:167], v[210:213], v[48:63]
	ds_read_b64_tr_b16 v[210:211], v202 offset:0x1400
	ds_read_b64_tr_b16 v[212:213], v202 offset:0x1c00
	s_waitcnt lgkmcnt(6)
	v_mfma_f32_32x32x16_bf16 v[48:63], v[168:171], v[238:241], v[48:63]
	ds_read_b64_tr_b16 v[238:239], v202 offset:0x2400
	ds_read_b64_tr_b16 v[240:241], v202 offset:0x2c00
	s_waitcnt lgkmcnt(6)
	v_mfma_f32_32x32x16_bf16 v[48:63], v[172:175], v[242:245], v[48:63]
	ds_read_b64_tr_b16 v[242:243], v202 offset:0x3400
	ds_read_b64_tr_b16 v[244:245], v202 offset:0x3c00
	s_waitcnt lgkmcnt(6)
	v_mfma_f32_32x32x16_bf16 v[32:47], v[160:163], v[180:183], v[32:47]
	ds_read_b64_tr_b16 v[180:181], v202 offset:0x600
	ds_read_b64_tr_b16 v[182:183], v202 offset:0xe00
	s_waitcnt lgkmcnt(6)
	v_mfma_f32_32x32x16_bf16 v[32:47], v[164:167], v[210:213], v[32:47]
	ds_read_b64_tr_b16 v[210:211], v202 offset:0x1600
	ds_read_b64_tr_b16 v[212:213], v202 offset:0x1e00
	s_waitcnt lgkmcnt(6)
	v_mfma_f32_32x32x16_bf16 v[32:47], v[168:171], v[238:241], v[32:47]
	ds_read_b64_tr_b16 v[238:239], v202 offset:0x2600
	ds_read_b64_tr_b16 v[240:241], v202 offset:0x2e00
	s_waitcnt lgkmcnt(6)
	v_mfma_f32_32x32x16_bf16 v[32:47], v[172:175], v[242:245], v[32:47]
	ds_read_b64_tr_b16 v[242:243], v202 offset:0x3600
	ds_read_b64_tr_b16 v[244:245], v202 offset:0x3e00
	s_waitcnt lgkmcnt(6)
	v_mfma_f32_32x32x16_bf16 v[16:31], v[160:163], v[180:183], v[16:31]
	v_max_f32_e32 v160, v81, v81
	v_max_f32_e32 v161, v80, v80
	v_max_f32_e32 v160, v161, v160
	v_max3_f32 v160, v160, v82, v83
	v_max3_f32 v160, v160, v84, v85
	v_max3_f32 v160, v160, v86, v87
	v_max3_f32 v160, v160, v88, v89
	v_max3_f32 v160, v160, v90, v91
	v_max3_f32 v160, v160, v92, v93
	s_waitcnt lgkmcnt(4)
	v_mfma_f32_32x32x16_bf16 v[16:31], v[164:167], v[210:213], v[16:31]
	v_max3_f32 v160, v160, v94, v95
	v_max3_f32 v160, v160, v64, v65
	v_max3_f32 v160, v160, v66, v67
	v_max3_f32 v160, v160, v68, v69
	v_max3_f32 v160, v160, v70, v71
	v_max3_f32 v160, v160, v72, v73
	v_max3_f32 v160, v160, v74, v75
	v_max3_f32 v160, v160, v76, v77
	s_waitcnt lgkmcnt(2)
	v_mfma_f32_32x32x16_bf16 v[16:31], v[168:171], v[238:241], v[16:31]
	v_max3_f32 v160, v160, v78, v79
	v_mov_b32_e32 v161, v160
	s_nop 1
	v_permlane32_swap_b32_e32 v160, v161
	v_max_f32_e32 v161, v161, v161
	v_max_f32_e32 v160, v160, v160
	v_max_f32_e32 v160, v160, v161
	v_sub_f32_e32 v161, v160, v235
	v_cmp_ge_f32_e32 vcc, s69, v161
	v_max_f32_e32 v161, v235, v235
	v_max_f32_e32 v161, v161, v160
	s_waitcnt lgkmcnt(0)
	v_mfma_f32_32x32x16_bf16 v[16:31], v[172:175], v[242:245], v[16:31]
	v_sub_f32_e32 v160, v235, v161
	v_mul_f32_e32 v160, 0x3e0293ee, v160
	v_exp_f32_e32 v160, v160
	s_cmp_eq_u64 vcc, exec
	s_cselect_b64 s[0:1], -1, 0
	s_barrier
	s_waitcnt vmcnt(4)
	v_cndmask_b32_e64 v160, v160, 1.0, s[0:1]
	v_cmp_gt_f32_e32 vcc, 1.0, v160
	ds_write_b128 v207, v[144:147] offset:16384
	ds_write_b128 v208, v[148:151] offset:16384
	ds_write_b128 v205, v[152:155] offset:49152
	ds_write_b128 v206, v[156:159] offset:49152
	s_cbranch_vccz .LBB0_668
	s_and_saveexec_b64 s[26:27], s[6:7]
	ds_write_b32 v200, v160 offset:128
	s_or_b64 exec, exec, s[26:27]
	s_waitcnt lgkmcnt(0)
	v_add_u32_e32 v156, v187, v178
	ds_read_b128 v[144:147], v156 offset:224
	ds_read_b128 v[148:151], v156 offset:192
	ds_read_b128 v[152:155], v156 offset:160
	ds_read_b128 v[156:159], v156 offset:128
	s_waitcnt lgkmcnt(3)
	v_pk_mul_f32 v[12:13], v[12:13], v[144:145]
	s_waitcnt lgkmcnt(2)
	v_pk_mul_f32 v[8:9], v[8:9], v[148:149]
	s_waitcnt lgkmcnt(1)
	v_pk_mul_f32 v[4:5], v[4:5], v[152:153]
	v_pk_mul_f32 v[14:15], v[14:15], v[146:147]
	v_pk_mul_f32 v[10:11], v[10:11], v[150:151]
	v_pk_mul_f32 v[6:7], v[6:7], v[154:155]
	s_waitcnt lgkmcnt(0)
	v_pk_mul_f32 v[2:3], v[2:3], v[158:159]
	v_pk_mul_f32 v[0:1], v[0:1], v[156:157]
	v_pk_mul_f32 v[60:61], v[60:61], v[144:145]
	v_pk_mul_f32 v[56:57], v[56:57], v[148:149]
	v_pk_mul_f32 v[52:53], v[52:53], v[152:153]
	v_pk_mul_f32 v[62:63], v[62:63], v[146:147]
	v_pk_mul_f32 v[58:59], v[58:59], v[150:151]
	v_pk_mul_f32 v[54:55], v[54:55], v[154:155]
	v_pk_mul_f32 v[50:51], v[50:51], v[158:159]
	v_pk_mul_f32 v[48:49], v[48:49], v[156:157]
	v_pk_mul_f32 v[44:45], v[44:45], v[144:145]
	v_pk_mul_f32 v[40:41], v[40:41], v[148:149]
	v_pk_mul_f32 v[36:37], v[36:37], v[152:153]
	v_pk_mul_f32 v[46:47], v[46:47], v[146:147]
	v_pk_mul_f32 v[42:43], v[42:43], v[150:151]
	v_pk_mul_f32 v[38:39], v[38:39], v[154:155]
	v_pk_mul_f32 v[34:35], v[34:35], v[158:159]
	v_pk_mul_f32 v[32:33], v[32:33], v[156:157]
	v_pk_mul_f32 v[28:29], v[28:29], v[144:145]
	v_pk_mul_f32 v[24:25], v[24:25], v[148:149]
	v_pk_mul_f32 v[20:21], v[20:21], v[152:153]
	v_pk_mul_f32 v[30:31], v[30:31], v[146:147]
	v_pk_mul_f32 v[26:27], v[26:27], v[150:151]
	v_pk_mul_f32 v[22:23], v[22:23], v[154:155]
	v_pk_mul_f32 v[18:19], v[18:19], v[158:159]
	v_pk_mul_f32 v[16:17], v[16:17], v[156:157]

.Latt_noload_gqa:
	s_waitcnt vmcnt(0)
	s_branch .LBB0_664

.LBB0_689:
	s_waitcnt lgkmcnt(0)
	ds_read_b64_tr_b16 v[204:205], v168 offset:0
	ds_read_b64_tr_b16 v[206:207], v168 offset:0x800
	ds_read_b64_tr_b16 v[226:227], v168 offset:0x1000
	ds_read_b64_tr_b16 v[228:229], v168 offset:0x1800
	ds_read_b64_tr_b16 v[230:231], v168 offset:0x2000
	ds_read_b64_tr_b16 v[232:233], v168 offset:0x2800
	ds_read_b64_tr_b16 v[234:235], v168 offset:0x3000
	ds_read_b64_tr_b16 v[236:237], v168 offset:0x3800
	s_nop 0
	s_waitcnt lgkmcnt(6)
	v_mfma_f32_32x32x16_bf16 v[0:15], v[144:147], v[204:207], v[0:15]
	ds_read_b64_tr_b16 v[204:205], v168 offset:0x200
	ds_read_b64_tr_b16 v[206:207], v168 offset:0xa00
	s_waitcnt lgkmcnt(6)
	v_mfma_f32_32x32x16_bf16 v[0:15], v[148:151], v[226:229], v[0:15]
	ds_read_b64_tr_b16 v[226:227], v168 offset:0x1200
	ds_read_b64_tr_b16 v[228:229], v168 offset:0x1a00
	s_waitcnt lgkmcnt(6)
	v_mfma_f32_32x32x16_bf16 v[0:15], v[152:155], v[230:233], v[0:15]
	ds_read_b64_tr_b16 v[230:231], v168 offset:0x2200
	ds_read_b64_tr_b16 v[232:233], v168 offset:0x2a00
	s_waitcnt lgkmcnt(6)
	v_mfma_f32_32x32x16_bf16 v[0:15], v[156:159], v[234:237], v[0:15]
	ds_read_b64_tr_b16 v[234:235], v168 offset:0x3200
	ds_read_b64_tr_b16 v[236:237], v168 offset:0x3a00
	s_waitcnt lgkmcnt(6)
	v_mfma_f32_32x32x16_bf16 v[48:63], v[144:147], v[204:207], v[48:63]
	ds_read_b64_tr_b16 v[204:205], v168 offset:0x400
	ds_read_b64_tr_b16 v[206:207], v168 offset:0xc00
	s_waitcnt lgkmcnt(6)
	v_mfma_f32_32x32x16_bf16 v[48:63], v[148:151], v[226:229], v[48:63]
	ds_read_b64_tr_b16 v[226:227], v168 offset:0x1400
	ds_read_b64_tr_b16 v[228:229], v168 offset:0x1c00
	s_waitcnt lgkmcnt(6)
	v_mfma_f32_32x32x16_bf16 v[48:63], v[152:155], v[230:233], v[48:63]
	ds_read_b64_tr_b16 v[230:231], v168 offset:0x2400
	ds_read_b64_tr_b16 v[232:233], v168 offset:0x2c00
	s_waitcnt lgkmcnt(6)
	v_mfma_f32_32x32x16_bf16 v[48:63], v[156:159], v[234:237], v[48:63]
	ds_read_b64_tr_b16 v[234:235], v168 offset:0x3400
	ds_read_b64_tr_b16 v[236:237], v168 offset:0x3c00
	s_waitcnt lgkmcnt(6)
	v_mfma_f32_32x32x16_bf16 v[32:47], v[144:147], v[204:207], v[32:47]
	ds_read_b64_tr_b16 v[204:205], v168 offset:0x600
	ds_read_b64_tr_b16 v[206:207], v168 offset:0xe00
	s_waitcnt lgkmcnt(6)
	v_mfma_f32_32x32x16_bf16 v[32:47], v[148:151], v[226:229], v[32:47]
	ds_read_b64_tr_b16 v[226:227], v168 offset:0x1600
	ds_read_b64_tr_b16 v[228:229], v168 offset:0x1e00
	s_waitcnt lgkmcnt(6)
	v_mfma_f32_32x32x16_bf16 v[32:47], v[152:155], v[230:233], v[32:47]
	ds_read_b64_tr_b16 v[230:231], v168 offset:0x2600
	ds_read_b64_tr_b16 v[232:233], v168 offset:0x2e00
	s_waitcnt lgkmcnt(6)
	v_mfma_f32_32x32x16_bf16 v[32:47], v[156:159], v[234:237], v[32:47]
	ds_read_b64_tr_b16 v[234:235], v168 offset:0x3600
	ds_read_b64_tr_b16 v[236:237], v168 offset:0x3e00
	s_waitcnt lgkmcnt(6)
	v_mfma_f32_32x32x16_bf16 v[16:31], v[144:147], v[204:207], v[16:31]
	v_max_f32_e32 v144, v81, v81
	v_max_f32_e32 v145, v80, v80
	v_max_f32_e32 v144, v145, v144
	v_max3_f32 v144, v144, v82, v83
	v_max3_f32 v144, v144, v84, v85
	v_max3_f32 v144, v144, v86, v87
	v_max3_f32 v144, v144, v88, v89
	v_max3_f32 v144, v144, v90, v91
	v_max3_f32 v144, v144, v92, v93
	s_waitcnt lgkmcnt(4)
	v_mfma_f32_32x32x16_bf16 v[16:31], v[148:151], v[226:229], v[16:31]
	v_max3_f32 v144, v144, v94, v95
	v_max3_f32 v144, v144, v64, v65
	v_max3_f32 v144, v144, v66, v67
	v_max3_f32 v144, v144, v68, v69
	v_max3_f32 v144, v144, v70, v71
	v_max3_f32 v144, v144, v72, v73
	v_max3_f32 v144, v144, v74, v75
	v_max3_f32 v144, v144, v76, v77
	s_waitcnt lgkmcnt(2)
	v_mfma_f32_32x32x16_bf16 v[16:31], v[152:155], v[230:233], v[16:31]
	v_max3_f32 v144, v144, v78, v79
	v_mov_b32_e32 v145, v144
	s_nop 1
	v_permlane32_swap_b32_e32 v144, v145
	v_max_f32_e32 v145, v145, v145
	v_max_f32_e32 v144, v144, v144
	v_max_f32_e32 v144, v144, v145
	v_sub_f32_e32 v145, v144, v200
	v_cmp_ge_f32_e32 vcc, s49, v145
	v_max_f32_e32 v145, v200, v200
	v_max_f32_e32 v145, v145, v144
	s_waitcnt lgkmcnt(0)
	v_mfma_f32_32x32x16_bf16 v[16:31], v[156:159], v[234:237], v[16:31]
	v_sub_f32_e32 v144, v200, v145
	v_mul_f32_e32 v144, 0x3e38aa3b, v144
	v_exp_f32_e32 v144, v144
	s_cmp_eq_u64 vcc, exec
	s_cselect_b64 s[0:1], -1, 0
	s_barrier
	s_waitcnt vmcnt(4)
	v_cndmask_b32_e64 v144, v144, 1.0, s[0:1]
	v_cmp_gt_f32_e32 vcc, 1.0, v144
	ds_write_b128 v173, v[128:131] offset:16384
	ds_write_b128 v174, v[132:135] offset:16384
	ds_write_b128 v171, v[136:139] offset:49152
	ds_write_b128 v172, v[140:143] offset:49152
	s_cbranch_vccz .LBB0_693
	s_and_saveexec_b64 s[38:39], s[6:7]
	ds_write_b32 v166, v144 offset:128
	s_or_b64 exec, exec, s[38:39]
	s_waitcnt lgkmcnt(0)
	v_add_u32_e32 v140, v161, v178
	ds_read_b128 v[128:131], v140 offset:224
	ds_read_b128 v[132:135], v140 offset:192
	ds_read_b128 v[136:139], v140 offset:160
	ds_read_b128 v[140:143], v140 offset:128
	s_waitcnt lgkmcnt(3)
	v_pk_mul_f32 v[12:13], v[12:13], v[128:129]
	s_waitcnt lgkmcnt(2)
	v_pk_mul_f32 v[8:9], v[8:9], v[132:133]
	s_waitcnt lgkmcnt(1)
	v_pk_mul_f32 v[4:5], v[4:5], v[136:137]
	v_pk_mul_f32 v[14:15], v[14:15], v[130:131]
	v_pk_mul_f32 v[10:11], v[10:11], v[134:135]
	v_pk_mul_f32 v[6:7], v[6:7], v[138:139]
	s_waitcnt lgkmcnt(0)
	v_pk_mul_f32 v[2:3], v[2:3], v[142:143]
	v_pk_mul_f32 v[0:1], v[0:1], v[140:141]
	v_pk_mul_f32 v[60:61], v[60:61], v[128:129]
	v_pk_mul_f32 v[56:57], v[56:57], v[132:133]
	v_pk_mul_f32 v[52:53], v[52:53], v[136:137]
	v_pk_mul_f32 v[62:63], v[62:63], v[130:131]
	v_pk_mul_f32 v[58:59], v[58:59], v[134:135]
	v_pk_mul_f32 v[54:55], v[54:55], v[138:139]
	v_pk_mul_f32 v[50:51], v[50:51], v[142:143]
	v_pk_mul_f32 v[48:49], v[48:49], v[140:141]
	v_pk_mul_f32 v[44:45], v[44:45], v[128:129]
	v_pk_mul_f32 v[40:41], v[40:41], v[132:133]
	v_pk_mul_f32 v[36:37], v[36:37], v[136:137]
	v_pk_mul_f32 v[46:47], v[46:47], v[130:131]
	v_pk_mul_f32 v[42:43], v[42:43], v[134:135]
	v_pk_mul_f32 v[38:39], v[38:39], v[138:139]
	v_pk_mul_f32 v[34:35], v[34:35], v[142:143]
	v_pk_mul_f32 v[32:33], v[32:33], v[140:141]
	v_pk_mul_f32 v[28:29], v[28:29], v[128:129]
	v_pk_mul_f32 v[24:25], v[24:25], v[132:133]
	v_pk_mul_f32 v[20:21], v[20:21], v[136:137]
	v_pk_mul_f32 v[30:31], v[30:31], v[130:131]
	v_pk_mul_f32 v[26:27], v[26:27], v[134:135]
	v_pk_mul_f32 v[22:23], v[22:23], v[138:139]
	v_pk_mul_f32 v[18:19], v[18:19], v[142:143]
	v_pk_mul_f32 v[16:17], v[16:17], v[140:141]

.LBB0_713:
	s_waitcnt lgkmcnt(0)
	ds_read_b64_tr_b16 v[204:205], v168 offset:0
	ds_read_b64_tr_b16 v[206:207], v168 offset:0x800
	ds_read_b64_tr_b16 v[226:227], v168 offset:0x1000
	ds_read_b64_tr_b16 v[228:229], v168 offset:0x1800
	ds_read_b64_tr_b16 v[230:231], v168 offset:0x2000
	ds_read_b64_tr_b16 v[232:233], v168 offset:0x2800
	ds_read_b64_tr_b16 v[234:235], v168 offset:0x3000
	ds_read_b64_tr_b16 v[236:237], v168 offset:0x3800
	s_nop 0
	s_waitcnt lgkmcnt(6)
	v_mfma_f32_32x32x16_bf16 v[32:47], v[144:147], v[204:207], v[32:47]
	ds_read_b64_tr_b16 v[204:205], v168 offset:0x200
	ds_read_b64_tr_b16 v[206:207], v168 offset:0xa00
	s_waitcnt lgkmcnt(6)
	v_mfma_f32_32x32x16_bf16 v[32:47], v[148:151], v[226:229], v[32:47]
	ds_read_b64_tr_b16 v[226:227], v168 offset:0x1200
	ds_read_b64_tr_b16 v[228:229], v168 offset:0x1a00
	s_waitcnt lgkmcnt(6)
	v_mfma_f32_32x32x16_bf16 v[32:47], v[152:155], v[230:233], v[32:47]
	ds_read_b64_tr_b16 v[230:231], v168 offset:0x2200
	ds_read_b64_tr_b16 v[232:233], v168 offset:0x2a00
	s_waitcnt lgkmcnt(6)
	v_mfma_f32_32x32x16_bf16 v[32:47], v[156:159], v[234:237], v[32:47]
	ds_read_b64_tr_b16 v[234:235], v168 offset:0x3200
	ds_read_b64_tr_b16 v[236:237], v168 offset:0x3a00
	s_waitcnt lgkmcnt(6)
	v_mfma_f32_32x32x16_bf16 v[48:63], v[144:147], v[204:207], v[48:63]
	ds_read_b64_tr_b16 v[204:205], v168 offset:0x400
	ds_read_b64_tr_b16 v[206:207], v168 offset:0xc00
	s_waitcnt lgkmcnt(6)
	v_mfma_f32_32x32x16_bf16 v[48:63], v[148:151], v[226:229], v[48:63]
	ds_read_b64_tr_b16 v[226:227], v168 offset:0x1400
	ds_read_b64_tr_b16 v[228:229], v168 offset:0x1c00
	s_waitcnt lgkmcnt(6)
	v_mfma_f32_32x32x16_bf16 v[48:63], v[152:155], v[230:233], v[48:63]
	ds_read_b64_tr_b16 v[230:231], v168 offset:0x2400
	ds_read_b64_tr_b16 v[232:233], v168 offset:0x2c00
	s_waitcnt lgkmcnt(6)
	v_mfma_f32_32x32x16_bf16 v[48:63], v[156:159], v[234:237], v[48:63]
	ds_read_b64_tr_b16 v[234:235], v168 offset:0x3400
	ds_read_b64_tr_b16 v[236:237], v168 offset:0x3c00
	s_waitcnt lgkmcnt(6)
	v_mfma_f32_32x32x16_bf16 v[16:31], v[144:147], v[204:207], v[16:31]
	ds_read_b64_tr_b16 v[204:205], v168 offset:0x600
	ds_read_b64_tr_b16 v[206:207], v168 offset:0xe00
	s_waitcnt lgkmcnt(6)
	v_mfma_f32_32x32x16_bf16 v[16:31], v[148:151], v[226:229], v[16:31]
	ds_read_b64_tr_b16 v[226:227], v168 offset:0x1600
	ds_read_b64_tr_b16 v[228:229], v168 offset:0x1e00
	s_waitcnt lgkmcnt(6)
	v_mfma_f32_32x32x16_bf16 v[16:31], v[152:155], v[230:233], v[16:31]
	ds_read_b64_tr_b16 v[230:231], v168 offset:0x2600
	ds_read_b64_tr_b16 v[232:233], v168 offset:0x2e00
	s_waitcnt lgkmcnt(6)
	v_mfma_f32_32x32x16_bf16 v[16:31], v[156:159], v[234:237], v[16:31]
	ds_read_b64_tr_b16 v[234:235], v168 offset:0x3600
	ds_read_b64_tr_b16 v[236:237], v168 offset:0x3e00
	s_waitcnt lgkmcnt(6)
	v_mfma_f32_32x32x16_bf16 v[0:15], v[144:147], v[204:207], v[0:15]
	v_max_f32_e32 v144, v81, v81
	v_max_f32_e32 v145, v80, v80
	v_max_f32_e32 v144, v145, v144
	v_max3_f32 v144, v144, v82, v83
	v_max3_f32 v144, v144, v84, v85
	v_max3_f32 v144, v144, v86, v87
	v_max3_f32 v144, v144, v88, v89
	v_max3_f32 v144, v144, v90, v91
	v_max3_f32 v144, v144, v92, v93
	s_waitcnt lgkmcnt(4)
	v_mfma_f32_32x32x16_bf16 v[0:15], v[148:151], v[226:229], v[0:15]
	v_max3_f32 v144, v144, v94, v95
	v_max3_f32 v144, v144, v64, v65
	v_max3_f32 v144, v144, v66, v67
	v_max3_f32 v144, v144, v68, v69
	v_max3_f32 v144, v144, v70, v71
	v_max3_f32 v144, v144, v72, v73
	v_max3_f32 v144, v144, v74, v75
	v_max3_f32 v144, v144, v76, v77
	s_waitcnt lgkmcnt(2)
	v_mfma_f32_32x32x16_bf16 v[0:15], v[152:155], v[230:233], v[0:15]
	v_max3_f32 v144, v144, v78, v79
	v_mov_b32_e32 v145, v144
	s_nop 1
	v_permlane32_swap_b32_e32 v144, v145
	v_max_f32_e32 v145, v145, v145
	v_max_f32_e32 v144, v144, v144
	v_max_f32_e32 v144, v144, v145
	v_sub_f32_e32 v145, v144, v200
	v_cmp_ge_f32_e32 vcc, s26, v145
	v_max_f32_e32 v145, v200, v200
	v_max_f32_e32 v145, v145, v144
	s_waitcnt lgkmcnt(0)
	v_mfma_f32_32x32x16_bf16 v[0:15], v[156:159], v[234:237], v[0:15]
	v_sub_f32_e32 v144, v200, v145
	v_mul_f32_e32 v144, 0x3e38aa3b, v144
	v_exp_f32_e32 v144, v144
	s_cmp_eq_u64 vcc, exec
	s_cselect_b64 s[0:1], -1, 0
	s_barrier
	s_waitcnt vmcnt(4)
	v_cndmask_b32_e64 v144, v144, 1.0, s[0:1]
	v_cmp_gt_f32_e32 vcc, 1.0, v144
	ds_write_b128 v173, v[128:131] offset:16384
	ds_write_b128 v174, v[132:135] offset:16384
	ds_write_b128 v171, v[136:139] offset:49152
	ds_write_b128 v172, v[140:143] offset:49152
	s_cbranch_vccz .LBB0_717
	s_and_saveexec_b64 s[22:23], s[6:7]
	ds_write_b32 v166, v144 offset:128
	s_or_b64 exec, exec, s[22:23]
	s_waitcnt lgkmcnt(0)
	v_add_u32_e32 v140, v161, v178
	ds_read_b128 v[128:131], v140 offset:224
	ds_read_b128 v[132:135], v140 offset:192
	ds_read_b128 v[136:139], v140 offset:160
	ds_read_b128 v[140:143], v140 offset:128
	s_waitcnt lgkmcnt(3)
	v_pk_mul_f32 v[44:45], v[44:45], v[128:129]
	s_waitcnt lgkmcnt(2)
	v_pk_mul_f32 v[40:41], v[40:41], v[132:133]
	s_waitcnt lgkmcnt(1)
	v_pk_mul_f32 v[36:37], v[36:37], v[136:137]
	v_pk_mul_f32 v[46:47], v[46:47], v[130:131]
	v_pk_mul_f32 v[42:43], v[42:43], v[134:135]
	v_pk_mul_f32 v[38:39], v[38:39], v[138:139]
	s_waitcnt lgkmcnt(0)
	v_pk_mul_f32 v[34:35], v[34:35], v[142:143]
	v_pk_mul_f32 v[32:33], v[32:33], v[140:141]
	v_pk_mul_f32 v[60:61], v[60:61], v[128:129]
	v_pk_mul_f32 v[56:57], v[56:57], v[132:133]
	v_pk_mul_f32 v[52:53], v[52:53], v[136:137]
	v_pk_mul_f32 v[62:63], v[62:63], v[130:131]
	v_pk_mul_f32 v[58:59], v[58:59], v[134:135]
	v_pk_mul_f32 v[54:55], v[54:55], v[138:139]
	v_pk_mul_f32 v[50:51], v[50:51], v[142:143]
	v_pk_mul_f32 v[48:49], v[48:49], v[140:141]
	v_pk_mul_f32 v[28:29], v[28:29], v[128:129]
	v_pk_mul_f32 v[24:25], v[24:25], v[132:133]
	v_pk_mul_f32 v[20:21], v[20:21], v[136:137]
	v_pk_mul_f32 v[30:31], v[30:31], v[130:131]
	v_pk_mul_f32 v[26:27], v[26:27], v[134:135]
	v_pk_mul_f32 v[22:23], v[22:23], v[138:139]
	v_pk_mul_f32 v[18:19], v[18:19], v[142:143]
	v_pk_mul_f32 v[16:17], v[16:17], v[140:141]
	v_pk_mul_f32 v[12:13], v[12:13], v[128:129]
	v_pk_mul_f32 v[8:9], v[8:9], v[132:133]
	v_pk_mul_f32 v[4:5], v[4:5], v[136:137]
	v_pk_mul_f32 v[14:15], v[14:15], v[130:131]
	v_pk_mul_f32 v[10:11], v[10:11], v[134:135]
	v_pk_mul_f32 v[6:7], v[6:7], v[138:139]
	v_pk_mul_f32 v[2:3], v[2:3], v[142:143]
	v_pk_mul_f32 v[0:1], v[0:1], v[140:141]
